# MODE-1 attention tiles: 32 serialised bias lookups replaced by extended-table batched ds_read2 (all 4 sites)
# speedup vs baseline: 1.0403x; 1.0403x over previous
; DI void task_nsa(const P& p, int layer, int task, bf16_t* sm, int dm) {
;     ...
;   __syncthreads();
;   for (int i = tid; i < 4 * 129; i += NTHR) {
;     const int r = i / 129, d = i % 129;
;     tabs[r * 132 + d] = ((const float*)(p.ws + O_TABS))[(12 + g * 4 + r) * 132 + d];
;   }
.LBB0_654:
	s_or_b64 exec, exec, s[0:1]
	v_mov_b32_e32 v0, v195
	s_and_b32 s40, s34, 1
	s_movk_i32 s0, 0x204
	s_barrier
	s_mul_i32 s100, s40, 0x840
	s_addk_i32 s100, 0x18c0
	s_add_u32 s36, s20, s100
	s_addc_u32 s37, s21, 0
	s_movk_i32 s100, 0x80
	s_movk_i32 s101, 0x200
	v_subrev_u32_e32 v247, 64, v195
	v_add_u32_e32 v248, 0x1c0, v195
	v_med3_i32 v249, v247, 0, s100
	v_med3_i32 v250, v248, 0, s100
	v_lshlrev_b32_e32 v249, 2, v249
	v_lshlrev_b32_e32 v250, 2, v250
	global_load_dword v196, v249, s[36:37]
	global_load_dword v197, v250, s[36:37]
	global_load_dword v198, v249, s[36:37] offset:528
	global_load_dword v199, v250, s[36:37] offset:528
	global_load_dword v200, v249, s[36:37] offset:1056
	global_load_dword v201, v250, s[36:37] offset:1056
	global_load_dword v202, v249, s[36:37] offset:1584
	global_load_dword v203, v250, s[36:37] offset:1584
	v_mov_b32_e32 v246, 0xf149f2ca
	v_lshlrev_b32_e32 v244, 2, v195
	v_add_u32_e32 v244, 0x1e000, v244
	s_waitcnt vmcnt(0)
	v_cmp_gt_u32_e64 s[98:99], s101, v247
	s_nop 1
	v_cndmask_b32_e64 v196, v246, v196, s[98:99]
	v_cndmask_b32_e64 v198, v246, v198, s[98:99]
	v_cndmask_b32_e64 v200, v246, v200, s[98:99]
	v_cndmask_b32_e64 v202, v246, v202, s[98:99]
	v_cmp_gt_u32_e64 s[98:99], s101, v248
	s_nop 1
	v_cndmask_b32_e64 v197, v246, v197, s[98:99]
	v_cndmask_b32_e64 v199, v246, v199, s[98:99]
	v_cndmask_b32_e64 v201, v246, v201, s[98:99]
	v_cndmask_b32_e64 v203, v246, v203, s[98:99]
	ds_write_b32 v244, v196
	ds_write_b32 v244, v197 offset:2048
	ds_write_b32 v244, v198 offset:4096
	ds_write_b32 v244, v199 offset:6144
	ds_write_b32 v244, v200 offset:8192
	ds_write_b32 v244, v201 offset:10240
	ds_write_b32 v244, v202 offset:12288
	ds_write_b32 v244, v203 offset:14336
	s_lshl_b32 s6, s40, 2
	v_cmp_gt_i32_e32 vcc, s0, v0
	s_barrier
	s_and_saveexec_b64 s[0:1], vcc
	s_cbranch_execz .LBB0_662
	v_max_i32_e32 v1, 4, v0
	v_sub_u32_e32 v1, v1, v0
	v_add_u32_e32 v2, 0x1ff, v1
	s_movk_i32 s2, 0x1ff
	v_cmp_lt_u32_e32 vcc, s2, v2
	s_mov_b64 s[4:5], -1
	v_mov_b32_e32 v1, v0
	s_and_saveexec_b64 s[2:3], vcc
	s_cbranch_execz .LBB0_659
	v_lshrrev_b32_e32 v1, 9, v2
	v_add_u32_e32 v4, 1, v1
	s_add_i32 s7, s6, 12
	v_and_b32_e32 v5, 0xfffffe, v4
	v_add_u32_e32 v1, 0x200, v0
	s_mov_b32 s8, s7
	s_mov_b64 s[4:5], 0
	v_mov_b32_e32 v6, v5
	v_mov_b64_e32 v[2:3], v[0:1]

; #define MFMA32(a, b, c) __builtin_amdgcn_mfma_f32_32x32x16_bf16((a), (b), (c), 0, 0, 0)
; DI float ex2(float x) { return __builtin_amdgcn_exp2f(x); }
; DI float xor32(float v) { return __shfl_xor(v, 32); }
; template <int NDT, int MODE, bool ALLON>
; DI void attn_tile(const bf16_t* Kl, int kst, const bf16_t* Vl, const bf16x8 (&q)[4], f32x16 (&O)[NDT], float& m, float& l,
;                   int kbase, int qp, int win, float cbias, const float* tab, bool lane_on) {
;     ...
;   for (int ks = 0; ks < 4; ++ks) {
;     const bf16x8 k0 = *(const bf16x8*)(Kl + lr * kst + ks * 16 + lh * 8);
;     const bf16x8 k1 = *(const bf16x8*)(Kl + (32 + lr) * kst + ks * 16 + lh * 8);
;     s[0] = MFMA32(k0, q[ks], s[0]);
;     s[1] = MFMA32(k1, q[ks], s[1]);
;   }
;   float alpha, psum = 0.f;
;   if (MODE == 0) {
;     float tmax = fmaxf(s[0][0], s[1][0]);
; #pragma unroll
;     for (int i = 1; i < 16; ++i) tmax = fmaxf(tmax, fmaxf(s[0][i], s[1][i]));
;     tmax = fmaxf(tmax, xor32(tmax)) + cbias;
;     if (!ALLON) tmax = lane_on ? tmax : -1e30f;
;     const float mn = fmaxf(m, tmax);
;     alpha = ex2(m - mn);
;     m = mn;
;     const float mc = (ALLON || lane_on) ? mn - cbias : 1e30f;
; #pragma unroll
;     for (int st = 0; st < 2; ++st)
; #pragma unroll
;       for (int i = 0; i < 16; ++i) { const float pe = ex2(s[st][i] - mc); psum += pe; s[st][i] = pe; }
;   } else {
;     float tmax = -1e30f;
; #pragma unroll
;     for (int st = 0; st < 2; ++st)
; #pragma unroll
;       for (int i = 0; i < 16; ++i) {
;         const int key = kbase + st * 32 + 8 * (i >> 2) + 4 * lh + (i & 3);
;         float v;
;         if (MODE == 1) {
;           const int dist = qp - key;
;           const bool ok = (ALLON || lane_on) && dist >= 0 && dist < win;
;           const int di = dist < 0 ? 0 : (dist > 128 ? 128 : dist);
;           v = ok ? s[st][i] + tab[di] : -1e30f;
;         } else {
;           v = (16 * key + 31 <= qp) ? s[st][i] : -1e30f;
;         }
;         s[st][i] = v;
;         tmax = fmaxf(tmax, v);
;       }
;     tmax = fmaxf(tmax, xor32(tmax));
.LBB0_727:
	s_andn2_saveexec_b64 s[28:29], s[28:29]
	s_cbranch_execz .LBB0_796
	s_nop 6
	v_mov_b32_e32 v0, v195
	v_mov_b32_e32 v55, 0xf149f2ca
	v_and_b32_e32 v1, 31, v0
	v_bfe_u32 v42, v0, 5, 1
	v_mul_u32_u24_e32 v0, 0x48, v1
	v_lshlrev_b32_e32 v33, 1, v0
	v_lshlrev_b32_e32 v0, 4, v42
	v_add3_u32 v43, s45, v33, v0
	ds_read_b128 v[0:3], v43 offset:4608
	ds_read_b128 v[4:7], v43
	ds_read_b128 v[34:37], v43 offset:32
	ds_read_b128 v[38:41], v43 offset:4640
	s_waitcnt lgkmcnt(2)
	v_mfma_f32_32x32x16_bf16 v[16:31], v[4:7], v[64:67], 0
	v_mov_b32_e32 v62, 0xf149f2ca
	v_mfma_f32_32x32x16_bf16 v[0:15], v[0:3], v[64:67], 0
	s_waitcnt lgkmcnt(1)
	v_mfma_f32_32x32x16_bf16 v[16:31], v[34:37], v[68:71], v[16:31]
	s_waitcnt lgkmcnt(0)
	v_mfma_f32_32x32x16_bf16 v[0:15], v[38:41], v[68:71], v[0:15]
	ds_read_b128 v[34:37], v43 offset:64
	ds_read_b128 v[38:41], v43 offset:4672
	s_waitcnt lgkmcnt(1)
	v_mfma_f32_32x32x16_bf16 v[16:31], v[34:37], v[72:75], v[16:31]
	s_waitcnt lgkmcnt(0)
	v_mfma_f32_32x32x16_bf16 v[0:15], v[38:41], v[72:75], v[0:15]
	ds_read_b128 v[34:37], v43 offset:96
	ds_read_b128 v[38:41], v43 offset:4704
	s_waitcnt lgkmcnt(1)
	v_mfma_f32_32x32x16_bf16 v[16:31], v[34:37], v[76:79], v[16:31]
	v_lshlrev_b32_e32 v34, 2, v42
	v_or_b32_e32 v32, v34, v32
	v_sub_u32_e32 v35, v134, v32
	v_bfe_u32 v245, v195, 6, 2
	v_lshlrev_b32_e32 v245, 12, v245
	v_add_u32_e32 v245, 0x1e014, v245
	v_lshl_add_u32 v244, v35, 2, v245
	v_subrev_u32_e32 v246, 20, v245
	v_cndmask_b32_e64 v244, v246, v244, s[4:5]
	s_waitcnt lgkmcnt(0)
	v_mfma_f32_32x32x16_bf16 v[0:15], v[38:41], v[76:79], v[0:15]
	ds_read2_b32 v[196:197], v244 offset0:59 offset1:58
	ds_read2_b32 v[198:199], v244 offset0:57 offset1:56
	ds_read2_b32 v[200:201], v244 offset0:51 offset1:50
	ds_read2_b32 v[202:203], v244 offset0:49 offset1:48
	ds_read2_b32 v[204:205], v244 offset0:43 offset1:42
	ds_read2_b32 v[206:207], v244 offset0:41 offset1:40
	ds_read2_b32 v[208:209], v244 offset0:35 offset1:34
	ds_read2_b32 v[210:211], v244 offset0:33 offset1:32
	ds_read2_b32 v[212:213], v244 offset0:27 offset1:26
	ds_read2_b32 v[214:215], v244 offset0:25 offset1:24
	ds_read2_b32 v[216:217], v244 offset0:19 offset1:18
	ds_read2_b32 v[218:219], v244 offset0:17 offset1:16
	ds_read2_b32 v[236:237], v244 offset0:11 offset1:10
	ds_read2_b32 v[238:239], v244 offset0:9 offset1:8
	ds_read2_b32 v[240:241], v244 offset0:3 offset1:2
	s_waitcnt lgkmcnt(14)
	v_add_f32_e32 v62, v16, v196
	v_add_f32_e32 v55, v17, v197
	ds_read2_b32 v[242:243], v244 offset0:1 offset1:0
	s_waitcnt lgkmcnt(14)
	v_add_f32_e32 v61, v18, v198
	v_add_f32_e32 v49, v19, v199
	s_waitcnt lgkmcnt(13)
	v_add_f32_e32 v60, v20, v200
	v_add_f32_e32 v47, v21, v201
	s_waitcnt lgkmcnt(12)
	v_add_f32_e32 v59, v22, v202
	v_add_f32_e32 v45, v23, v203
	s_waitcnt lgkmcnt(11)
	v_add_f32_e32 v58, v24, v204
	v_add_f32_e32 v43, v25, v205
	s_waitcnt lgkmcnt(10)
	v_add_f32_e32 v57, v26, v206
	v_add_f32_e32 v42, v27, v207
	s_waitcnt lgkmcnt(9)
	v_add_f32_e32 v56, v28, v208
	v_add_f32_e32 v41, v29, v209
	s_waitcnt lgkmcnt(8)
	v_add_f32_e32 v54, v30, v210
	v_add_f32_e32 v40, v31, v211
	s_waitcnt lgkmcnt(7)
	v_add_f32_e32 v52, v0, v212
	v_add_f32_e32 v39, v1, v213
	s_waitcnt lgkmcnt(6)
	v_add_f32_e32 v51, v2, v214
	v_add_f32_e32 v38, v3, v215
	s_waitcnt lgkmcnt(5)
	v_add_f32_e32 v48, v4, v216
	v_add_f32_e32 v37, v5, v217
	s_waitcnt lgkmcnt(4)
	v_add_f32_e32 v46, v6, v218
	v_add_f32_e32 v35, v7, v219
	s_waitcnt lgkmcnt(3)
	v_add_f32_e32 v44, v8, v236
	v_add_f32_e32 v36, v9, v237
	s_waitcnt lgkmcnt(2)
	v_add_f32_e32 v53, v10, v238
	v_add_f32_e32 v50, v11, v239
	s_waitcnt lgkmcnt(1)
	v_add_f32_e32 v142, v12, v240
	v_add_f32_e32 v63, v13, v241
	s_waitcnt lgkmcnt(0)
	v_add_f32_e32 v144, v14, v242
	v_add_f32_e32 v143, v15, v243
	v_max3_f32 v0, v62, s93, v55
	v_max3_f32 v0, v0, v61, v49
	v_max3_f32 v0, v0, v60, v47
	v_max3_f32 v0, v0, v59, v45
	v_max3_f32 v0, v0, v58, v43
	v_max3_f32 v0, v0, v57, v42
	v_max3_f32 v0, v0, v56, v41
	v_max3_f32 v0, v0, v54, v40
	v_max3_f32 v0, v0, v52, v39
	v_max3_f32 v0, v0, v51, v38
	v_max3_f32 v0, v0, v48, v37
	v_max3_f32 v0, v0, v46, v35
	v_max3_f32 v0, v0, v44, v36
	v_max3_f32 v0, v0, v53, v50
	v_max3_f32 v0, v0, v142, v63
	v_max3_f32 v0, v0, v144, v143
	ds_bpermute_b32 v1, v91, v0
	s_waitcnt lgkmcnt(0)
	v_max3_f32 v141, v88, v0, v1
	v_sub_f32_e32 v0, v88, v141
	v_exp_f32_e32 v32, v0
	s_nop 0
	v_cmp_neq_f32_e32 vcc, 1.0, v32
	s_cbranch_vccz .LBB0_800
	v_pk_mul_f32 v[160:161], v[160:161], v[32:33] op_sel_hi:[1,0]
	v_pk_mul_f32 v[162:163], v[162:163], v[32:33] op_sel_hi:[1,0]
	v_pk_mul_f32 v[164:165], v[164:165], v[32:33] op_sel_hi:[1,0]
	v_pk_mul_f32 v[166:167], v[166:167], v[32:33] op_sel_hi:[1,0]
	v_pk_mul_f32 v[168:169], v[168:169], v[32:33] op_sel_hi:[1,0]
	v_pk_mul_f32 v[170:171], v[170:171], v[32:33] op_sel_hi:[1,0]
	v_pk_mul_f32 v[172:173], v[172:173], v[32:33] op_sel_hi:[1,0]
	v_pk_mul_f32 v[174:175], v[174:175], v[32:33] op_sel_hi:[1,0]
	v_pk_mul_f32 v[176:177], v[176:177], v[32:33] op_sel_hi:[1,0]
	v_pk_mul_f32 v[178:179], v[178:179], v[32:33] op_sel_hi:[1,0]
	v_pk_mul_f32 v[180:181], v[180:181], v[32:33] op_sel_hi:[1,0]
	v_pk_mul_f32 v[182:183], v[182:183], v[32:33] op_sel_hi:[1,0]
	v_pk_mul_f32 v[184:185], v[184:185], v[32:33] op_sel_hi:[1,0]
	v_pk_mul_f32 v[186:187], v[186:187], v[32:33] op_sel_hi:[1,0]
	v_pk_mul_f32 v[188:189], v[188:189], v[32:33] op_sel_hi:[1,0]
	v_pk_mul_f32 v[190:191], v[190:191], v[32:33] op_sel_hi:[1,0]
	s_cbranch_execnz .LBB0_795

; #define MFMA32(a, b, c) __builtin_amdgcn_mfma_f32_32x32x16_bf16((a), (b), (c), 0, 0, 0)
; DI float ex2(float x) { return __builtin_amdgcn_exp2f(x); }
; DI float xor32(float v) { return __shfl_xor(v, 32); }
; template <int NDT, int MODE, bool ALLON>
; DI void attn_tile(const bf16_t* Kl, int kst, const bf16_t* Vl, const bf16x8 (&q)[4], f32x16 (&O)[NDT], float& m, float& l,
;                   int kbase, int qp, int win, float cbias, const float* tab, bool lane_on) {
;     ...
;   for (int ks = 0; ks < 4; ++ks) {
;     const bf16x8 k0 = *(const bf16x8*)(Kl + lr * kst + ks * 16 + lh * 8);
;     const bf16x8 k1 = *(const bf16x8*)(Kl + (32 + lr) * kst + ks * 16 + lh * 8);
;     s[0] = MFMA32(k0, q[ks], s[0]);
;     s[1] = MFMA32(k1, q[ks], s[1]);
;   }
;   float alpha, psum = 0.f;
;   if (MODE == 0) {
;     float tmax = fmaxf(s[0][0], s[1][0]);
; #pragma unroll
;     for (int i = 1; i < 16; ++i) tmax = fmaxf(tmax, fmaxf(s[0][i], s[1][i]));
;     tmax = fmaxf(tmax, xor32(tmax)) + cbias;
;     if (!ALLON) tmax = lane_on ? tmax : -1e30f;
;     const float mn = fmaxf(m, tmax);
;     alpha = ex2(m - mn);
;     m = mn;
;     const float mc = (ALLON || lane_on) ? mn - cbias : 1e30f;
; #pragma unroll
;     for (int st = 0; st < 2; ++st)
; #pragma unroll
;       for (int i = 0; i < 16; ++i) { const float pe = ex2(s[st][i] - mc); psum += pe; s[st][i] = pe; }
;   } else {
;     float tmax = -1e30f;
; #pragma unroll
;     for (int st = 0; st < 2; ++st)
; #pragma unroll
;       for (int i = 0; i < 16; ++i) {
;         const int key = kbase + st * 32 + 8 * (i >> 2) + 4 * lh + (i & 3);
;         float v;
;         if (MODE == 1) {
;           const int dist = qp - key;
;           const bool ok = (ALLON || lane_on) && dist >= 0 && dist < win;
;           const int di = dist < 0 ? 0 : (dist > 128 ? 128 : dist);
;           v = ok ? s[st][i] + tab[di] : -1e30f;
;         } else {
;           v = (16 * key + 31 <= qp) ? s[st][i] : -1e30f;
;         }
;         s[st][i] = v;
;         tmax = fmaxf(tmax, v);
;       }
;     tmax = fmaxf(tmax, xor32(tmax));
.LBB0_810:
	v_cmp_le_i32_e32 vcc, s6, v138
	v_cmp_ge_i32_e64 s[0:1], s6, v127
	s_and_b64 s[0:1], vcc, s[0:1]
	s_waitcnt lgkmcnt(0)
	s_barrier
	s_and_saveexec_b64 s[28:29], s[0:1]
	s_cbranch_execz .LBB0_807
	v_cmp_gt_i32_e32 vcc, s6, v137
	v_cmp_le_i32_e64 s[0:1], s6, v128
	s_or_b64 s[0:1], vcc, s[0:1]
	s_and_saveexec_b64 s[30:31], s[0:1]
	s_xor_b64 s[0:1], exec, s[30:31]
	s_cbranch_execz .LBB0_880
	v_mov_b32_e32 v0, v195
	v_mov_b32_e32 v63, 0xf149f2ca
	v_and_b32_e32 v1, 31, v0
	v_bfe_u32 v34, v0, 5, 1
	v_mul_u32_u24_e32 v0, 0x48, v1
	v_lshlrev_b32_e32 v33, 1, v0
	v_lshlrev_b32_e32 v0, 4, v34
	v_add3_u32 v32, s25, v33, v0
	ds_read_b128 v[0:3], v32
	ds_read_b128 v[36:39], v32 offset:32
	v_mov_b32_e32 v134, 0xf149f2ca
	s_waitcnt lgkmcnt(1)
	v_mfma_f32_32x32x16_bf16 v[16:31], v[0:3], v[64:67], 0
	ds_read_b128 v[0:3], v32 offset:4608
	s_waitcnt lgkmcnt(1)
	v_mfma_f32_32x32x16_bf16 v[16:31], v[36:39], v[68:71], v[16:31]
	ds_read_b128 v[36:39], v32 offset:4640
	s_waitcnt lgkmcnt(1)
	v_mfma_f32_32x32x16_bf16 v[0:15], v[0:3], v[64:67], 0
	s_waitcnt lgkmcnt(0)
	v_mfma_f32_32x32x16_bf16 v[0:15], v[36:39], v[68:71], v[0:15]
	ds_read_b128 v[36:39], v32 offset:64
	s_waitcnt lgkmcnt(0)
	v_mfma_f32_32x32x16_bf16 v[16:31], v[36:39], v[72:75], v[16:31]
	ds_read_b128 v[36:39], v32 offset:4672
	s_waitcnt lgkmcnt(0)
	v_mfma_f32_32x32x16_bf16 v[0:15], v[36:39], v[72:75], v[0:15]
	ds_read_b128 v[36:39], v32 offset:96
	s_waitcnt lgkmcnt(0)
	v_mfma_f32_32x32x16_bf16 v[16:31], v[36:39], v[76:79], v[16:31]
	ds_read_b128 v[36:39], v32 offset:4704
	v_lshlrev_b32_e32 v32, 2, v34
	v_sub_u32_e32 v32, v129, v32
	v_add_u32_e32 v35, 59, v32
	v_bfe_u32 v245, v195, 6, 2
	v_lshlrev_b32_e32 v245, 12, v245
	v_add_u32_e32 v245, 0x1e014, v245
	v_lshl_add_u32 v244, v35, 2, v245
	s_waitcnt lgkmcnt(0)
	v_mfma_f32_32x32x16_bf16 v[0:15], v[36:39], v[76:79], v[0:15]
	ds_read2_b32 v[196:197], v244 offset0:59 offset1:58
	ds_read2_b32 v[198:199], v244 offset0:57 offset1:56
	ds_read2_b32 v[200:201], v244 offset0:51 offset1:50
	ds_read2_b32 v[202:203], v244 offset0:49 offset1:48
	ds_read2_b32 v[204:205], v244 offset0:43 offset1:42
	ds_read2_b32 v[206:207], v244 offset0:41 offset1:40
	ds_read2_b32 v[208:209], v244 offset0:35 offset1:34
	ds_read2_b32 v[210:211], v244 offset0:33 offset1:32
	ds_read2_b32 v[212:213], v244 offset0:27 offset1:26
	ds_read2_b32 v[214:215], v244 offset0:25 offset1:24
	ds_read2_b32 v[216:217], v244 offset0:19 offset1:18
	ds_read2_b32 v[218:219], v244 offset0:17 offset1:16
	ds_read2_b32 v[236:237], v244 offset0:11 offset1:10
	ds_read2_b32 v[238:239], v244 offset0:9 offset1:8
	ds_read2_b32 v[240:241], v244 offset0:3 offset1:2
	s_waitcnt lgkmcnt(14)
	v_add_f32_e32 v134, v16, v196
	v_add_f32_e32 v63, v17, v197
	ds_read2_b32 v[242:243], v244 offset0:1 offset1:0
	s_waitcnt lgkmcnt(14)
	v_add_f32_e32 v133, v18, v198
	v_add_f32_e32 v58, v19, v199
	s_waitcnt lgkmcnt(13)
	v_add_f32_e32 v132, v20, v200
	v_add_f32_e32 v56, v21, v201
	s_waitcnt lgkmcnt(12)
	v_add_f32_e32 v62, v22, v202
	v_add_f32_e32 v54, v23, v203
	s_waitcnt lgkmcnt(11)
	v_add_f32_e32 v60, v24, v204
	v_add_f32_e32 v51, v25, v205
	s_waitcnt lgkmcnt(10)
	v_add_f32_e32 v57, v26, v206
	v_add_f32_e32 v48, v27, v207
	s_waitcnt lgkmcnt(9)
	v_add_f32_e32 v55, v28, v208
	v_add_f32_e32 v46, v29, v209
	s_waitcnt lgkmcnt(8)
	v_add_f32_e32 v52, v30, v210
	v_add_f32_e32 v43, v31, v211
	s_waitcnt lgkmcnt(7)
	v_add_f32_e32 v49, v0, v212
	v_add_f32_e32 v40, v1, v213
	s_waitcnt lgkmcnt(6)
	v_add_f32_e32 v47, v2, v214
	v_add_f32_e32 v38, v3, v215
	s_waitcnt lgkmcnt(5)
	v_add_f32_e32 v45, v4, v216
	v_add_f32_e32 v37, v5, v217
	s_waitcnt lgkmcnt(4)
	v_add_f32_e32 v42, v6, v218
	v_add_f32_e32 v36, v7, v219
	s_waitcnt lgkmcnt(3)
	v_add_f32_e32 v39, v8, v236
	v_add_f32_e32 v35, v9, v237
	s_waitcnt lgkmcnt(2)
	v_add_f32_e32 v44, v10, v238
	v_add_f32_e32 v41, v11, v239
	s_waitcnt lgkmcnt(1)
	v_add_f32_e32 v53, v12, v240
	v_add_f32_e32 v50, v13, v241
	s_waitcnt lgkmcnt(0)
	v_add_f32_e32 v61, v14, v242
	v_add_f32_e32 v59, v15, v243
	v_max3_f32 v0, v134, s93, v63
	v_max3_f32 v0, v0, v133, v58
	v_max3_f32 v0, v0, v132, v56
	v_max3_f32 v0, v0, v62, v54
	v_max3_f32 v0, v0, v60, v51
	v_max3_f32 v0, v0, v57, v48
	v_max3_f32 v0, v0, v55, v46
	v_max3_f32 v0, v0, v52, v43
	v_max3_f32 v0, v0, v49, v40
	v_max3_f32 v0, v0, v47, v38
	v_max3_f32 v0, v0, v45, v37
	v_max3_f32 v0, v0, v42, v36
	v_max3_f32 v0, v0, v39, v35
	v_max3_f32 v0, v0, v44, v41
	v_max3_f32 v0, v0, v53, v50
	v_max3_f32 v0, v0, v61, v59
	ds_bpermute_b32 v1, v91, v0
	s_waitcnt lgkmcnt(0)
	v_max3_f32 v130, v126, v0, v1
	v_sub_f32_e32 v0, v126, v130
	v_exp_f32_e32 v32, v0
	s_nop 0
	v_cmp_neq_f32_e32 vcc, 1.0, v32
	s_cbranch_vccz .LBB0_883
	v_pk_mul_f32 v[160:161], v[160:161], v[32:33] op_sel_hi:[1,0]
	v_pk_mul_f32 v[162:163], v[162:163], v[32:33] op_sel_hi:[1,0]
	v_pk_mul_f32 v[164:165], v[164:165], v[32:33] op_sel_hi:[1,0]
	v_pk_mul_f32 v[166:167], v[166:167], v[32:33] op_sel_hi:[1,0]
	v_pk_mul_f32 v[168:169], v[168:169], v[32:33] op_sel_hi:[1,0]
	v_pk_mul_f32 v[170:171], v[170:171], v[32:33] op_sel_hi:[1,0]
	v_pk_mul_f32 v[172:173], v[172:173], v[32:33] op_sel_hi:[1,0]
	v_pk_mul_f32 v[174:175], v[174:175], v[32:33] op_sel_hi:[1,0]
	v_pk_mul_f32 v[176:177], v[176:177], v[32:33] op_sel_hi:[1,0]
	v_pk_mul_f32 v[178:179], v[178:179], v[32:33] op_sel_hi:[1,0]
	v_pk_mul_f32 v[180:181], v[180:181], v[32:33] op_sel_hi:[1,0]
	v_pk_mul_f32 v[182:183], v[182:183], v[32:33] op_sel_hi:[1,0]
	v_pk_mul_f32 v[184:185], v[184:185], v[32:33] op_sel_hi:[1,0]
	v_pk_mul_f32 v[186:187], v[186:187], v[32:33] op_sel_hi:[1,0]
	v_pk_mul_f32 v[188:189], v[188:189], v[32:33] op_sel_hi:[1,0]
	v_pk_mul_f32 v[190:191], v[190:191], v[32:33] op_sel_hi:[1,0]
	s_cbranch_execnz .LBB0_879

; DI void task_attnB(const P& p, int layer, int task, bf16_t* sm, int dm) {
;     ...
;   float* tabs = (float*)((unsigned char*)sm + 36864);
;   __syncthreads();
;   for (int i = tid; i < 4 * 129; i += NTHR) {
;     const int r = i / 129, d = i % 129;
;     tabs[r * 132 + d] = ((const float*)(p.ws + O_TABS))[(4 + g * 4 + r) * 132 + d];
;   }
.LBB0_886:
	s_and_b64 vcc, exec, s[0:1]
	s_cbranch_vccz .LBB0_970
	v_mov_b32_e32 v0, v195
	s_and_b32 s6, s34, 1
	s_movk_i32 s0, 0x204
	s_lshl_b32 s7, s6, 2
	v_cmp_gt_i32_e32 vcc, s0, v0
	s_barrier
	s_mul_i32 s100, s6, 0x840
	s_addk_i32 s100, 0x840
	s_add_u32 s36, s20, s100
	s_addc_u32 s37, s21, 0
	s_movk_i32 s100, 0x80
	s_movk_i32 s101, 0x80
	v_subrev_u32_e32 v247, 64, v195
	v_med3_i32 v249, v247, 0, s100
	v_lshlrev_b32_e32 v249, 2, v249
	global_load_dword v196, v249, s[36:37]
	global_load_dword v197, v249, s[36:37] offset:528
	global_load_dword v198, v249, s[36:37] offset:1056
	global_load_dword v199, v249, s[36:37] offset:1584
	v_mov_b32_e32 v246, 0xf149f2ca
	v_lshlrev_b32_e32 v244, 2, v195
	v_add_u32_e32 v244, 0x1e000, v244
	s_waitcnt vmcnt(0)
	v_cmp_gt_u32_e64 s[98:99], s101, v247
	s_nop 1
	v_cndmask_b32_e64 v196, v246, v196, s[98:99]
	v_cndmask_b32_e64 v197, v246, v197, s[98:99]
	v_cndmask_b32_e64 v198, v246, v198, s[98:99]
	v_cndmask_b32_e64 v199, v246, v199, s[98:99]
	ds_write_b32 v244, v196
	ds_write_b32 v244, v197 offset:4096
	ds_write_b32 v244, v198 offset:8192
	ds_write_b32 v244, v199 offset:12288
	s_and_saveexec_b64 s[0:1], vcc
	s_cbranch_execz .LBB0_895
	v_max_i32_e32 v1, 4, v0
	v_sub_u32_e32 v1, v1, v0
	v_add_u32_e32 v2, 0x1ff, v1
	s_movk_i32 s2, 0x1ff
	v_cmp_lt_u32_e32 vcc, s2, v2
	s_mov_b64 s[4:5], -1
	v_mov_b32_e32 v1, v0
	s_and_saveexec_b64 s[2:3], vcc
	s_cbranch_execz .LBB0_892
	v_lshrrev_b32_e32 v1, 9, v2
	v_add_u32_e32 v4, 1, v1
	s_add_i32 s8, s7, 4
	v_and_b32_e32 v5, 0xfffffe, v4
	v_add_u32_e32 v1, 0x200, v0
	s_mov_b32 s9, s8
	s_mov_b64 s[4:5], 0
	v_mov_b32_e32 v6, v5
	v_mov_b64_e32 v[2:3], v[0:1]

; #define MFMA32(a, b, c) __builtin_amdgcn_mfma_f32_32x32x16_bf16((a), (b), (c), 0, 0, 0)
; DI float ex2(float x) { return __builtin_amdgcn_exp2f(x); }
; DI float xor32(float v) { return __shfl_xor(v, 32); }
; template <int NDT, int MODE, bool ALLON>
; DI void attn_tile(const bf16_t* Kl, int kst, const bf16_t* Vl, const bf16x8 (&q)[4], f32x16 (&O)[NDT], float& m, float& l,
;                   int kbase, int qp, int win, float cbias, const float* tab, bool lane_on) {
;     ...
;   for (int ks = 0; ks < 4; ++ks) {
;     const bf16x8 k0 = *(const bf16x8*)(Kl + lr * kst + ks * 16 + lh * 8);
;     const bf16x8 k1 = *(const bf16x8*)(Kl + (32 + lr) * kst + ks * 16 + lh * 8);
;     s[0] = MFMA32(k0, q[ks], s[0]);
;     s[1] = MFMA32(k1, q[ks], s[1]);
;   }
;   float alpha, psum = 0.f;
;   if (MODE == 0) {
;     float tmax = fmaxf(s[0][0], s[1][0]);
; #pragma unroll
;     for (int i = 1; i < 16; ++i) tmax = fmaxf(tmax, fmaxf(s[0][i], s[1][i]));
;     tmax = fmaxf(tmax, xor32(tmax)) + cbias;
;     if (!ALLON) tmax = lane_on ? tmax : -1e30f;
;     const float mn = fmaxf(m, tmax);
;     alpha = ex2(m - mn);
;     m = mn;
;     const float mc = (ALLON || lane_on) ? mn - cbias : 1e30f;
; #pragma unroll
;     for (int st = 0; st < 2; ++st)
; #pragma unroll
;       for (int i = 0; i < 16; ++i) { const float pe = ex2(s[st][i] - mc); psum += pe; s[st][i] = pe; }
;   } else {
;     float tmax = -1e30f;
; #pragma unroll
;     for (int st = 0; st < 2; ++st)
; #pragma unroll
;       for (int i = 0; i < 16; ++i) {
;         const int key = kbase + st * 32 + 8 * (i >> 2) + 4 * lh + (i & 3);
;         float v;
;         if (MODE == 1) {
;           const int dist = qp - key;
;           const bool ok = (ALLON || lane_on) && dist >= 0 && dist < win;
;           const int di = dist < 0 ? 0 : (dist > 128 ? 128 : dist);
;           v = ok ? s[st][i] + tab[di] : -1e30f;
;         } else {
;           v = (16 * key + 31 <= qp) ? s[st][i] : -1e30f;
;         }
;         s[st][i] = v;
;         tmax = fmaxf(tmax, v);
;       }
;     tmax = fmaxf(tmax, xor32(tmax));
.LBB0_902:
	v_cmp_le_i32_e32 vcc, s6, v94
	v_cmp_ge_i32_e64 s[0:1], s6, v93
	s_and_b64 s[28:29], vcc, s[0:1]
	s_waitcnt lgkmcnt(0)
	s_barrier
	s_and_saveexec_b64 s[0:1], s[28:29]
	s_cbranch_execz .LBB0_899
	v_mov_b32_e32 v0, v195
	v_mov_b32_e32 v131, 0xf149f2ca
	v_and_b32_e32 v1, 31, v0
	v_bfe_u32 v108, v0, 5, 1
	v_mul_u32_u24_e32 v0, 0x48, v1
	v_lshlrev_b32_e32 v99, 1, v0
	v_lshlrev_b32_e32 v109, 4, v108
	v_add3_u32 v110, s31, v99, v109
	ds_read_b128 v[0:3], v110 offset:4608
	ds_read_b128 v[4:7], v110
	ds_read_b128 v[100:103], v110 offset:32
	ds_read_b128 v[104:107], v110 offset:4640
	s_waitcnt lgkmcnt(2)
	v_mfma_f32_32x32x16_bf16 v[16:31], v[4:7], v[32:35], 0
	v_mov_b32_e32 v133, 0xf149f2ca
	v_mfma_f32_32x32x16_bf16 v[0:15], v[0:3], v[32:35], 0
	s_waitcnt lgkmcnt(1)
	v_mfma_f32_32x32x16_bf16 v[16:31], v[100:103], v[36:39], v[16:31]
	s_waitcnt lgkmcnt(0)
	v_mfma_f32_32x32x16_bf16 v[0:15], v[104:107], v[36:39], v[0:15]
	ds_read_b128 v[100:103], v110 offset:64
	ds_read_b128 v[104:107], v110 offset:4672
	s_waitcnt lgkmcnt(1)
	v_mfma_f32_32x32x16_bf16 v[16:31], v[100:103], v[40:43], v[16:31]
	s_waitcnt lgkmcnt(0)
	v_mfma_f32_32x32x16_bf16 v[0:15], v[104:107], v[40:43], v[0:15]
	ds_read_b128 v[100:103], v110 offset:96
	ds_read_b128 v[104:107], v110 offset:4704
	s_waitcnt lgkmcnt(1)
	v_mfma_f32_32x32x16_bf16 v[16:31], v[100:103], v[44:47], v[16:31]
	v_lshlrev_b32_e32 v100, 2, v108
	v_sub_u32_e32 v134, v96, v100
	v_add_u32_e32 v101, 59, v134
	v_bfe_u32 v245, v195, 6, 2
	v_lshlrev_b32_e32 v245, 12, v245
	v_add_u32_e32 v245, 0x1e014, v245
	v_lshl_add_u32 v244, v101, 2, v245
	v_sub_u32_e32 v101, v97, v109
	s_waitcnt lgkmcnt(0)
	v_mfma_f32_32x32x16_bf16 v[0:15], v[104:107], v[44:47], v[0:15]
	ds_read2_b32 v[196:197], v244 offset0:59 offset1:58
	ds_read2_b32 v[198:199], v244 offset0:57 offset1:56
	ds_read2_b32 v[200:201], v244 offset0:51 offset1:50
	ds_read2_b32 v[202:203], v244 offset0:49 offset1:48
	ds_read2_b32 v[204:205], v244 offset0:43 offset1:42
	ds_read2_b32 v[206:207], v244 offset0:41 offset1:40
	ds_read2_b32 v[208:209], v244 offset0:35 offset1:34
	ds_read2_b32 v[210:211], v244 offset0:33 offset1:32
	ds_read2_b32 v[212:213], v244 offset0:27 offset1:26
	ds_read2_b32 v[214:215], v244 offset0:25 offset1:24
	ds_read2_b32 v[216:217], v244 offset0:19 offset1:18
	ds_read2_b32 v[218:219], v244 offset0:17 offset1:16
	ds_read2_b32 v[236:237], v244 offset0:11 offset1:10
	ds_read2_b32 v[238:239], v244 offset0:9 offset1:8
	ds_read2_b32 v[240:241], v244 offset0:3 offset1:2
	s_waitcnt lgkmcnt(14)
	v_add_f32_e32 v133, v16, v196
	v_add_f32_e32 v131, v17, v197
	ds_read2_b32 v[242:243], v244 offset0:1 offset1:0
	s_waitcnt lgkmcnt(14)
	v_add_f32_e32 v132, v18, v198
	v_add_f32_e32 v128, v19, v199
	s_waitcnt lgkmcnt(13)
	v_add_f32_e32 v130, v20, v200
	v_add_f32_e32 v126, v21, v201
	s_waitcnt lgkmcnt(12)
	v_add_f32_e32 v129, v22, v202
	v_add_f32_e32 v124, v23, v203
	s_waitcnt lgkmcnt(11)
	v_add_f32_e32 v127, v24, v204
	v_add_f32_e32 v122, v25, v205
	s_waitcnt lgkmcnt(10)
	v_add_f32_e32 v125, v26, v206
	v_add_f32_e32 v120, v27, v207
	s_waitcnt lgkmcnt(9)
	v_add_f32_e32 v123, v28, v208
	v_add_f32_e32 v116, v29, v209
	s_waitcnt lgkmcnt(8)
	v_add_f32_e32 v121, v30, v210
	v_add_f32_e32 v114, v31, v211
	s_waitcnt lgkmcnt(7)
	v_add_f32_e32 v118, v0, v212
	v_add_f32_e32 v110, v1, v213
	s_waitcnt lgkmcnt(6)
	v_add_f32_e32 v115, v2, v214
	v_add_f32_e32 v108, v3, v215
	s_waitcnt lgkmcnt(5)
	v_add_f32_e32 v112, v4, v216
	v_add_f32_e32 v104, v5, v217
	s_waitcnt lgkmcnt(4)
	v_add_f32_e32 v109, v6, v218
	v_add_f32_e32 v103, v7, v219
	s_waitcnt lgkmcnt(3)
	v_add_f32_e32 v105, v8, v236
	v_add_f32_e32 v102, v9, v237
	s_waitcnt lgkmcnt(2)
	v_add_f32_e32 v107, v10, v238
	v_add_f32_e32 v106, v11, v239
	s_waitcnt lgkmcnt(1)
	v_add_f32_e32 v113, v12, v240
	v_add_f32_e32 v111, v13, v241
	s_waitcnt lgkmcnt(0)
	v_add_f32_e32 v119, v14, v242
	v_add_f32_e32 v117, v15, v243
	v_max3_f32 v0, v133, s93, v131
	v_max3_f32 v0, v0, v132, v128
	v_max3_f32 v0, v0, v130, v126
	v_max3_f32 v0, v0, v129, v124
	v_max3_f32 v0, v0, v127, v122
	v_max3_f32 v0, v0, v125, v120
	v_max3_f32 v0, v0, v123, v116
	v_max3_f32 v0, v0, v121, v114
	v_max3_f32 v0, v0, v118, v110
	v_max3_f32 v0, v0, v115, v108
	v_max3_f32 v0, v0, v112, v104
	v_max3_f32 v0, v0, v109, v103
	v_and_b32_e32 v2, 64, v231
	v_max3_f32 v0, v0, v105, v102
	v_xor_b32_e32 v1, 32, v231
	v_add_u32_e32 v2, 64, v2
	v_max3_f32 v0, v0, v107, v106
	v_cmp_lt_i32_e32 vcc, v1, v2
	v_max3_f32 v0, v0, v113, v111
	v_max3_f32 v0, v0, v119, v117
	v_cndmask_b32_e32 v1, v231, v1, vcc
	v_lshlrev_b32_e32 v1, 2, v1
	ds_bpermute_b32 v1, v1, v0
	s_waitcnt lgkmcnt(0)
	v_max3_f32 v101, v90, v0, v1
	v_sub_f32_e32 v0, v90, v101
	v_exp_f32_e32 v90, v0
	s_nop 0
	v_cmp_neq_f32_e32 vcc, 1.0, v90
	s_cbranch_vccz .LBB0_969
	v_pk_mul_f32 v[0:1], v[86:87], v[90:91] op_sel_hi:[1,0]
	v_pk_mul_f32 v[2:3], v[88:89], v[90:91] op_sel_hi:[1,0]
	v_pk_mul_f32 v[4:5], v[84:85], v[90:91] op_sel_hi:[1,0]
	v_pk_mul_f32 v[6:7], v[82:83], v[90:91] op_sel_hi:[1,0]
	v_pk_mul_f32 v[8:9], v[80:81], v[90:91] op_sel_hi:[1,0]
	v_pk_mul_f32 v[10:11], v[76:77], v[90:91] op_sel_hi:[1,0]
	v_pk_mul_f32 v[12:13], v[72:73], v[90:91] op_sel_hi:[1,0]
	v_pk_mul_f32 v[14:15], v[68:69], v[90:91] op_sel_hi:[1,0]
	v_pk_mul_f32 v[16:17], v[78:79], v[90:91] op_sel_hi:[1,0]
	v_pk_mul_f32 v[18:19], v[74:75], v[90:91] op_sel_hi:[1,0]
	v_pk_mul_f32 v[20:21], v[70:71], v[90:91] op_sel_hi:[1,0]
	v_pk_mul_f32 v[22:23], v[66:67], v[90:91] op_sel_hi:[1,0]
	v_pk_mul_f32 v[24:25], v[64:65], v[90:91] op_sel_hi:[1,0]
	v_pk_mul_f32 v[26:27], v[62:63], v[90:91] op_sel_hi:[1,0]
	v_pk_mul_f32 v[28:29], v[60:61], v[90:91] op_sel_hi:[1,0]
	v_pk_mul_f32 v[30:31], v[58:59], v[90:91] op_sel_hi:[1,0]
	s_cbranch_execnz .LBB0_898
	s_branch .LBB0_897

; DI void task_attnA(const P& p, int layer, int task, bf16_t* sm, int dm) {
;     ...
;   float* tab = (float*)((unsigned char*)sm + 71680);
;   bf16x8* qlds = (bf16x8*)((unsigned char*)sm + 72704) + wv * 256 + lane;
;   float* xbuf = (float*)((unsigned char*)sm);
;   __syncthreads();
;   if (tid < 129) tab[tid] = ((const float*)(p.ws + O_TABS))[h * 132 + tid];
;   const int q0 = qb * 128, qmin = q0 + qs * 32, qp = qmin + lr;
;   bf16_t* aq = (bf16_t*)(p.ws + O_AQ);
;   {
;     const bf16_t* qptr = aq + (size_t)(b * S_ + qp) * 512 + h * 128 + c * 64 + lh * 8;
; #pragma unroll
;     for (int ks = 0; ks < 4; ++ks) qlds[ks * 64] = *(const bf16x8*)(qptr + ks * 16);
;   }
;   f32x16 O[4];
; #pragma unroll
;   for (int dt = 0; dt < 4; ++dt)
; #pragma unroll
;     for (int i = 0; i < 16; ++i) O[dt][i] = 0.f;
;   float m = -1e30f, l = 0.f;
;   const bf16_t* kg = (const bf16_t*)(p.ws + O_AK) + (size_t)b * S_ * 512 + h * 128;
;   const bf16_t* vg = (const bf16_t*)(p.ws + O_AVT) + (size_t)((b * 4 + h) * 128) * S_;
;   u32x4 rk0, rk1, rv0, rv1;
;     ...
;   const int kt_hi = 2 * qb + 1;
;   A_GLOAD(0, 0) A_GLOAD(1, 0)
.LBB0_974:
	s_or_b64 exec, exec, s[0:1]
	s_mul_i32 s100, s2, 0x210
	s_add_u32 s36, s20, s100
	s_addc_u32 s37, s21, 0
	s_movk_i32 s100, 0x80
	s_mov_b32 s101, 0x40000000
	v_subrev_u32_e32 v247, 64, v195
	v_med3_i32 v249, v247, 0, s100
	v_lshlrev_b32_e32 v249, 2, v249
	global_load_dword v196, v249, s[36:37]
	v_mov_b32_e32 v246, 0xf149f2ca
	v_lshlrev_b32_e32 v244, 2, v195
	v_add_u32_e32 v244, 0x1e000, v244
	s_waitcnt vmcnt(0)
	v_cmp_gt_u32_e64 s[98:99], s101, v247
	s_nop 1
	v_cndmask_b32_e64 v196, v246, v196, s[98:99]
	ds_write_b32 v244, v196
	s_add_i32 s3, s34, -16
	s_lshr_b32 s0, s3, 4
	s_xor_b32 s4, s0, 31
	v_ashrrev_i32_e32 v0, 2, v138
	s_lshl_b32 s5, s4, 7
	v_and_b32_e32 v27, 0xffffffe0, v0
	v_and_b32_e32 v139, 31, v138
	v_add_u32_e32 v28, s5, v27
	s_bfe_u32 s0, s34, 0x20002
	v_or_b32_e32 v0, v28, v139
	v_lshl_add_u32 v0, s0, 12, v0
	s_lshl_b32 s66, s2, 8
	s_lshl_b32 s0, s0, 22
	s_add_u32 s0, s56, s0
	v_ashrrev_i32_e32 v16, 4, v138
	s_addc_u32 s1, s57, 0
	v_ashrrev_i32_e32 v17, 31, v16
	s_add_u32 s0, s0, s66
	v_lshlrev_b64 v[18:19], 10, v[16:17]
	v_lshlrev_b32_e32 v17, 3, v138
	s_addc_u32 s1, s1, 0
	s_lshl_b32 s2, s3, 20
	v_and_b32_e32 v20, 0x78, v17
	s_and_b32 s2, s2, 0xf00000
	v_readlane_b32 s6, v253, 50
	v_lshlrev_b32_e32 v126, 1, v20
	v_ashrrev_i32_e32 v20, 3, v138
	v_readlane_b32 s7, v253, 51
	s_add_u32 s2, s6, s2
	v_ashrrev_i32_e32 v21, 31, v20
	v_ashrrev_i32_e32 v1, 31, v0
	s_addc_u32 s3, s7, 0
	v_lshlrev_b64 v[22:23], 13, v[20:21]
	v_and_b32_e32 v17, 56, v17
	v_ashrrev_i32_e32 v26, 6, v138
	v_lshlrev_b64 v[0:1], 10, v[0:1]
	v_lshl_add_u64 v[22:23], s[2:3], 0, v[22:23]
	v_lshlrev_b32_e32 v128, 1, v17
	v_mov_b32_e32 v129, v193
	v_add_u32_e32 v17, 0x200, v138
	v_and_b32_e32 v140, 1, v26
	v_lshl_add_u64 v[0:1], s[58:59], 0, v[0:1]
	v_lshl_add_u64 v[130:131], v[22:23], 0, v[128:129]
	v_ashrrev_i32_e32 v22, 4, v17
	v_bfe_u32 v137, v138, 5, 1
	v_lshl_add_u64 v[124:125], v[0:1], 0, s[66:67]
	v_lshlrev_b32_e32 v192, 7, v140
	v_ashrrev_i32_e32 v23, 31, v22
	v_lshl_add_u64 v[0:1], v[124:125], 0, v[192:193]
	v_lshlrev_b32_e32 v192, 4, v137
	v_lshl_add_u64 v[18:19], s[0:1], 0, v[18:19]
	v_mov_b32_e32 v127, v193
	v_lshlrev_b64 v[24:25], 10, v[22:23]
	v_lshl_add_u64 v[12:13], v[0:1], 0, v[192:193]
	v_lshl_add_u64 v[18:19], v[18:19], 0, v[126:127]
	v_lshl_add_u64 v[24:25], s[0:1], 0, v[24:25]
	global_load_dwordx4 v[0:3], v[12:13], off
	global_load_dwordx4 v[4:7], v[12:13], off offset:32
	global_load_dwordx4 v[8:11], v[12:13], off offset:64
	s_nop 0
	global_load_dwordx4 v[12:15], v[12:13], off offset:96
	v_lshl_add_u64 v[24:25], v[24:25], 0, v[126:127]
	global_load_dwordx4 v[96:99], v[18:19], off
	global_load_dwordx4 v[104:107], v[24:25], off
	v_ashrrev_i32_e32 v18, 3, v17
	v_ashrrev_i32_e32 v19, 31, v18
	v_lshlrev_b64 v[24:25], 13, v[18:19]
	v_lshl_add_u64 v[24:25], s[2:3], 0, v[24:25]
	v_lshl_add_u64 v[132:133], v[24:25], 0, v[128:129]
	global_load_dwordx4 v[100:103], v[130:131], off
	global_load_dwordx4 v[108:111], v[132:133], off
	v_and_b32_e32 v17, 63, v138
	v_lshlrev_b32_e32 v19, 12, v26
	v_lshlrev_b32_e32 v17, 4, v17
	v_readlane_b32 s3, v255, 5
	v_mov_b32_e32 v48, v193
	v_mov_b32_e32 v49, v193
	s_movk_i32 s2, 0x110
	v_add3_u32 v143, s3, v19, v17
	v_lshl_add_u64 v[134:135], s[0:1], 0, v[126:127]
	s_sub_i32 s0, s5, 59
	v_mov_b32_e32 v50, v193
	v_mul_lo_u32 v129, v16, s2
	v_mul_lo_u32 v141, v20, s89
	v_add_u32_e32 v142, 64, v16
	v_mul_lo_u32 v145, v22, s2
	v_mul_lo_u32 v146, v18, s89
	v_add_u32_e32 v147, 64, v22
	v_or_b32_e32 v148, 31, v28
	v_add_u32_e32 v149, 0xffffff41, v28
	s_lshl_b32 s6, s4, 1
	s_mov_b32 s66, 0
	v_add3_u32 v127, s0, v27, v139
	v_mov_b32_e32 v51, v193
	v_mov_b32_e32 v52, v193
	v_mov_b32_e32 v53, v193
	v_mov_b32_e32 v54, v193
	v_mov_b32_e32 v55, v193
	v_mov_b32_e32 v56, v193
	s_waitcnt vmcnt(7)
	ds_write_b128 v143, v[0:3]
	s_waitcnt vmcnt(6)
	ds_write_b128 v143, v[4:7] offset:1024
	s_waitcnt vmcnt(5)
	ds_write_b128 v143, v[8:11] offset:2048
	s_waitcnt vmcnt(4)
	ds_write_b128 v143, v[12:15] offset:3072
	v_mov_b32_e32 v57, v193
	v_mov_b32_e32 v58, v193
	v_mov_b32_e32 v59, v193
	v_mov_b32_e32 v60, v193
	v_mov_b32_e32 v61, v193
	v_mov_b32_e32 v62, v193
	v_mov_b32_e32 v63, v193
	v_mov_b64_e32 v[32:33], v[48:49]
	v_mov_b64_e32 v[16:17], v[48:49]
	v_mov_b64_e32 v[0:1], v[48:49]
	v_lshlrev_b32_e32 v144, 6, v140
	s_add_i32 s7, s6, 2
	v_mov_b32_e32 v154, 0xf149f2ca
	v_mov_b32_e32 v151, 0
	v_mov_b64_e32 v[34:35], v[50:51]
	v_mov_b64_e32 v[36:37], v[52:53]
	v_mov_b64_e32 v[38:39], v[54:55]
	v_mov_b64_e32 v[40:41], v[56:57]
	v_mov_b64_e32 v[42:43], v[58:59]
	v_mov_b64_e32 v[44:45], v[60:61]
	v_mov_b64_e32 v[46:47], v[62:63]
	v_mov_b64_e32 v[18:19], v[50:51]
	v_mov_b64_e32 v[20:21], v[52:53]
	v_mov_b64_e32 v[22:23], v[54:55]
	v_mov_b64_e32 v[24:25], v[56:57]
	v_mov_b64_e32 v[26:27], v[58:59]
	v_mov_b64_e32 v[28:29], v[60:61]
	v_mov_b64_e32 v[30:31], v[62:63]
	v_mov_b64_e32 v[2:3], v[50:51]
	v_mov_b64_e32 v[4:5], v[52:53]
	v_mov_b64_e32 v[6:7], v[54:55]
	v_mov_b64_e32 v[8:9], v[56:57]
	v_mov_b64_e32 v[10:11], v[58:59]
	v_mov_b64_e32 v[12:13], v[60:61]
	v_mov_b64_e32 v[14:15], v[62:63]
	s_mov_b32 s8, s66
	s_branch .LBB0_978

; #define MFMA32(a, b, c) __builtin_amdgcn_mfma_f32_32x32x16_bf16((a), (b), (c), 0, 0, 0)
; DI float ex2(float x) { return __builtin_amdgcn_exp2f(x); }
; DI float xor32(float v) { return __shfl_xor(v, 32); }
; template <int NDT, int MODE, bool ALLON>
; DI void attn_tile(const bf16_t* Kl, int kst, const bf16_t* Vl, const bf16x8 (&q)[4], f32x16 (&O)[NDT], float& m, float& l,
;                   int kbase, int qp, int win, float cbias, const float* tab, bool lane_on) {
;     ...
;   for (int ks = 0; ks < 4; ++ks) {
;     const bf16x8 k0 = *(const bf16x8*)(Kl + lr * kst + ks * 16 + lh * 8);
;     const bf16x8 k1 = *(const bf16x8*)(Kl + (32 + lr) * kst + ks * 16 + lh * 8);
;     s[0] = MFMA32(k0, q[ks], s[0]);
;     s[1] = MFMA32(k1, q[ks], s[1]);
;   }
;   float alpha, psum = 0.f;
;   if (MODE == 0) {
;     float tmax = fmaxf(s[0][0], s[1][0]);
; #pragma unroll
;     for (int i = 1; i < 16; ++i) tmax = fmaxf(tmax, fmaxf(s[0][i], s[1][i]));
;     tmax = fmaxf(tmax, xor32(tmax)) + cbias;
;     if (!ALLON) tmax = lane_on ? tmax : -1e30f;
;     const float mn = fmaxf(m, tmax);
;     alpha = ex2(m - mn);
;     m = mn;
;     const float mc = (ALLON || lane_on) ? mn - cbias : 1e30f;
; #pragma unroll
;     for (int st = 0; st < 2; ++st)
; #pragma unroll
;       for (int i = 0; i < 16; ++i) { const float pe = ex2(s[st][i] - mc); psum += pe; s[st][i] = pe; }
;   } else {
;     float tmax = -1e30f;
; #pragma unroll
;     for (int st = 0; st < 2; ++st)
; #pragma unroll
;       for (int i = 0; i < 16; ++i) {
;         const int key = kbase + st * 32 + 8 * (i >> 2) + 4 * lh + (i & 3);
;         float v;
;         if (MODE == 1) {
;           const int dist = qp - key;
;           const bool ok = (ALLON || lane_on) && dist >= 0 && dist < win;
;           const int di = dist < 0 ? 0 : (dist > 128 ? 128 : dist);
;           v = ok ? s[st][i] + tab[di] : -1e30f;
;         } else {
;           v = (16 * key + 31 <= qp) ? s[st][i] : -1e30f;
;         }
;         s[st][i] = v;
;         tmax = fmaxf(tmax, v);
;       }
;     tmax = fmaxf(tmax, xor32(tmax));
.LBB0_985:
	s_andn2_saveexec_b64 s[2:3], s[2:3]
	s_cbranch_execz .LBB0_976
	v_mov_b32_e32 v68, v195
	s_nop 0
	v_and_b32_e32 v152, 31, v68
	v_bfe_u32 v153, v68, 5, 1
	v_mul_u32_u24_e32 v68, 0x110, v152
	v_lshlrev_b32_e32 v70, 4, v153
	v_add3_u32 v150, v69, v68, v70
	ds_read_b128 v[68:71], v150
	ds_read_b128 v[156:159], v150 offset:32
	s_waitcnt lgkmcnt(1)
	v_mfma_f32_32x32x16_bf16 v[80:95], v[68:71], v[64:67], 0
	ds_read_b128 v[68:71], v150 offset:8704
	s_waitcnt lgkmcnt(1)
	v_mfma_f32_32x32x16_bf16 v[80:95], v[156:159], v[120:123], v[80:95]
	ds_read_b128 v[156:159], v150 offset:8736
	s_waitcnt lgkmcnt(1)
	v_mfma_f32_32x32x16_bf16 v[64:79], v[68:71], v[64:67], 0
	s_waitcnt lgkmcnt(0)
	v_mfma_f32_32x32x16_bf16 v[64:79], v[156:159], v[120:123], v[64:79]
	ds_read_b128 v[120:123], v150 offset:64
	ds_read_b128 v[156:159], v150 offset:8800
	s_waitcnt lgkmcnt(1)
	v_mfma_f32_32x32x16_bf16 v[80:95], v[120:123], v[116:119], v[80:95]
	ds_read_b128 v[120:123], v150 offset:8768
	s_waitcnt lgkmcnt(0)
	v_mfma_f32_32x32x16_bf16 v[64:79], v[120:123], v[116:119], v[64:79]
	ds_read_b128 v[116:119], v150 offset:96
	v_mov_b32_e32 v120, 0xf149f2ca
	s_waitcnt lgkmcnt(0)
	v_mfma_f32_32x32x16_bf16 v[80:95], v[116:119], v[112:115], v[80:95]
	v_lshlrev_b32_e32 v116, 2, v153
	v_sub_u32_e32 v123, v127, v116
	v_add_u32_e32 v117, 59, v123
	v_mov_b32_e32 v245, 0x1e014
	v_lshl_add_u32 v244, v117, 2, v245
	v_mov_b32_e32 v116, 0xf149f2ca
	v_mfma_f32_32x32x16_bf16 v[64:79], v[156:159], v[112:115], v[64:79]
	ds_read2_b32 v[196:197], v244 offset0:59 offset1:58
	ds_read2_b32 v[198:199], v244 offset0:57 offset1:56
	ds_read2_b32 v[200:201], v244 offset0:51 offset1:50
	ds_read2_b32 v[202:203], v244 offset0:49 offset1:48
	ds_read2_b32 v[204:205], v244 offset0:43 offset1:42
	ds_read2_b32 v[206:207], v244 offset0:41 offset1:40
	ds_read2_b32 v[208:209], v244 offset0:35 offset1:34
	ds_read2_b32 v[210:211], v244 offset0:33 offset1:32
	ds_read2_b32 v[212:213], v244 offset0:27 offset1:26
	ds_read2_b32 v[214:215], v244 offset0:25 offset1:24
	ds_read2_b32 v[216:217], v244 offset0:19 offset1:18
	ds_read2_b32 v[218:219], v244 offset0:17 offset1:16
	ds_read2_b32 v[236:237], v244 offset0:11 offset1:10
	ds_read2_b32 v[238:239], v244 offset0:9 offset1:8
	ds_read2_b32 v[240:241], v244 offset0:3 offset1:2
	s_waitcnt lgkmcnt(14)
	v_add_f32_e32 v120, v80, v196
	v_add_f32_e32 v116, v81, v197
	ds_read2_b32 v[242:243], v244 offset0:1 offset1:0
	s_waitcnt lgkmcnt(14)
	v_add_f32_e32 v119, v82, v198
	v_add_f32_e32 v114, v83, v199
	s_waitcnt lgkmcnt(13)
	v_add_f32_e32 v118, v84, v200
	v_add_f32_e32 v113, v85, v201
	s_waitcnt lgkmcnt(12)
	v_add_f32_e32 v117, v86, v202
	v_add_f32_e32 v112, v87, v203
	s_waitcnt lgkmcnt(11)
	v_add_f32_e32 v115, v88, v204
	v_add_f32_e32 v85, v89, v205
	s_waitcnt lgkmcnt(10)
	v_add_f32_e32 v88, v90, v206
	v_add_f32_e32 v83, v91, v207
	s_waitcnt lgkmcnt(9)
	v_add_f32_e32 v87, v92, v208
	v_add_f32_e32 v81, v93, v209
	s_waitcnt lgkmcnt(8)
	v_add_f32_e32 v86, v94, v210
	v_add_f32_e32 v80, v95, v211
	s_waitcnt lgkmcnt(7)
	v_add_f32_e32 v84, v64, v212
	v_add_f32_e32 v82, v65, v213
	s_waitcnt lgkmcnt(6)
	v_add_f32_e32 v89, v66, v214
	v_add_f32_e32 v65, v67, v215
	s_waitcnt lgkmcnt(5)
	v_add_f32_e32 v67, v68, v216
	v_add_f32_e32 v66, v69, v217
	s_waitcnt lgkmcnt(4)
	v_add_f32_e32 v69, v70, v218
	v_add_f32_e32 v68, v71, v219
	s_waitcnt lgkmcnt(3)
	v_add_f32_e32 v71, v72, v236
	v_add_f32_e32 v70, v73, v237
	s_waitcnt lgkmcnt(2)
	v_add_f32_e32 v73, v74, v238
	v_add_f32_e32 v72, v75, v239
	s_waitcnt lgkmcnt(1)
	v_add_f32_e32 v92, v76, v240
	v_add_f32_e32 v91, v77, v241
	s_waitcnt lgkmcnt(0)
	v_add_f32_e32 v122, v78, v242
	v_add_f32_e32 v121, v79, v243
	v_max3_f32 v64, v120, s93, v116
	v_max3_f32 v64, v64, v119, v114
	v_max3_f32 v64, v64, v118, v113
	v_max3_f32 v64, v64, v117, v112
	v_max3_f32 v64, v64, v115, v85
	v_max3_f32 v64, v64, v88, v83
	v_max3_f32 v64, v64, v87, v81
	v_max3_f32 v64, v64, v86, v80
	v_max3_f32 v64, v64, v84, v82
	v_max3_f32 v64, v64, v89, v65
	v_max3_f32 v64, v64, v67, v66
	v_max3_f32 v64, v64, v69, v68
	v_and_b32_e32 v75, 64, v231
	v_max3_f32 v64, v64, v71, v70
	v_xor_b32_e32 v74, 32, v231
	v_add_u32_e32 v75, 64, v75
	v_max3_f32 v64, v64, v73, v72
	v_cmp_lt_i32_e32 vcc, v74, v75
	v_max3_f32 v64, v64, v92, v91
	v_max3_f32 v64, v64, v122, v121
	v_cndmask_b32_e32 v74, v231, v74, vcc
	v_lshlrev_b32_e32 v74, 2, v74
	ds_bpermute_b32 v74, v74, v64
	s_waitcnt lgkmcnt(0)
	v_max3_f32 v150, v154, v64, v74
	v_sub_f32_e32 v64, v154, v150
	v_exp_f32_e32 v64, v64
	s_nop 0
	v_cmp_neq_f32_e32 vcc, 1.0, v64
	s_cbranch_vccz .LBB0_975
	v_pk_mul_f32 v[62:63], v[62:63], v[64:65] op_sel_hi:[1,0]
	v_pk_mul_f32 v[60:61], v[60:61], v[64:65] op_sel_hi:[1,0]
	v_pk_mul_f32 v[58:59], v[58:59], v[64:65] op_sel_hi:[1,0]
	v_pk_mul_f32 v[56:57], v[56:57], v[64:65] op_sel_hi:[1,0]
	v_pk_mul_f32 v[54:55], v[54:55], v[64:65] op_sel_hi:[1,0]
	v_pk_mul_f32 v[52:53], v[52:53], v[64:65] op_sel_hi:[1,0]
	v_pk_mul_f32 v[50:51], v[50:51], v[64:65] op_sel_hi:[1,0]
	v_pk_mul_f32 v[48:49], v[48:49], v[64:65] op_sel_hi:[1,0]
	v_pk_mul_f32 v[46:47], v[46:47], v[64:65] op_sel_hi:[1,0]
	v_pk_mul_f32 v[44:45], v[44:45], v[64:65] op_sel_hi:[1,0]
	v_pk_mul_f32 v[42:43], v[42:43], v[64:65] op_sel_hi:[1,0]
	v_pk_mul_f32 v[40:41], v[40:41], v[64:65] op_sel_hi:[1,0]
	v_pk_mul_f32 v[38:39], v[38:39], v[64:65] op_sel_hi:[1,0]
	v_pk_mul_f32 v[36:37], v[36:37], v[64:65] op_sel_hi:[1,0]
	v_pk_mul_f32 v[34:35], v[34:35], v[64:65] op_sel_hi:[1,0]
	v_pk_mul_f32 v[32:33], v[32:33], v[64:65] op_sel_hi:[1,0]
	v_pk_mul_f32 v[30:31], v[30:31], v[64:65] op_sel_hi:[1,0]
	v_pk_mul_f32 v[28:29], v[28:29], v[64:65] op_sel_hi:[1,0]
	v_pk_mul_f32 v[26:27], v[26:27], v[64:65] op_sel_hi:[1,0]
	v_pk_mul_f32 v[24:25], v[24:25], v[64:65] op_sel_hi:[1,0]
	v_pk_mul_f32 v[22:23], v[22:23], v[64:65] op_sel_hi:[1,0]
	v_pk_mul_f32 v[20:21], v[20:21], v[64:65] op_sel_hi:[1,0]
	v_pk_mul_f32 v[18:19], v[18:19], v[64:65] op_sel_hi:[1,0]
	v_pk_mul_f32 v[16:17], v[16:17], v[64:65] op_sel_hi:[1,0]
	v_pk_mul_f32 v[14:15], v[14:15], v[64:65] op_sel_hi:[1,0]
	v_pk_mul_f32 v[12:13], v[12:13], v[64:65] op_sel_hi:[1,0]
	v_pk_mul_f32 v[10:11], v[10:11], v[64:65] op_sel_hi:[1,0]
	v_pk_mul_f32 v[8:9], v[8:9], v[64:65] op_sel_hi:[1,0]
	v_pk_mul_f32 v[6:7], v[6:7], v[64:65] op_sel_hi:[1,0]
	v_pk_mul_f32 v[4:5], v[4:5], v[64:65] op_sel_hi:[1,0]
	v_pk_mul_f32 v[2:3], v[2:3], v[64:65] op_sel_hi:[1,0]
	v_pk_mul_f32 v[0:1], v[0:1], v[64:65] op_sel_hi:[1,0]
	s_branch .LBB0_975
